# v40 plus accumulator zeroing via 64 v_mov_b64 instead of 128 v_mov_b32 per GEMM unit
# speedup vs baseline: 1.0158x; 1.0055x over previous
; template <class Epi, class Sched, bool ALIGN_EPI = false, bool SP2 = false>
; __device__ __forceinline__ void gemm_phase(PG8_LAS unsigned char* lds, const Gemm g, const Sched& S, const Epi& E) {
;     ...
;         const bool has_next = S.next(ui + 1, nxt);
;         const char* nA = has_next ? (const char*)g.A + (size_t)nxt.pm * tstep : cA; const char* nB = has_next ? (const char*)g.Bt + (size_t)nxt.pn * tstep : cB;
;     ...
; #pragma unroll
;         for (int a = 0; a < 2; ++a)
; #pragma unroll
;             for (int b = 0; b < 2; ++b)
; #pragma unroll
;                 for (int m = 0; m < 4; ++m)
; #pragma unroll
;                     for (int n = 0; n < 2; ++n) acc[a][b][m][n] = (f32x4){0.f, 0.f, 0.f, 0.f};
;         cur = nxt; cA = nA; cB = nB; ++ui;
.LBB0_126:
	s_ashr_i32 s73, s72, 31
	s_lshl_b64 s[12:13], s[72:73], 20
	s_add_u32 s82, s40, s12
	s_addc_u32 s83, s41, s13
	s_and_b64 s[12:13], s[4:5], exec
	s_cselect_b32 s12, s83, s91
	s_cselect_b32 s13, s82, s90
	s_ashr_i32 s71, s70, 31
	s_lshl_b64 s[66:67], s[70:71], 20
	s_add_u32 s86, s78, s66
	s_addc_u32 s87, s79, s67
	s_and_b64 s[66:67], s[4:5], exec
	s_cselect_b32 s71, s87, s93
	s_cselect_b32 s73, s86, s92
	s_add_u32 s90, s90, 0x80080
	s_addc_u32 s91, s91, 0
	s_add_u32 vcc_lo, s92, 0x100
	v_mov_b64_e32 v[0:1], 0
	v_mov_b64_e32 v[2:3], 0
	v_mov_b64_e32 v[4:5], 0
	v_mov_b64_e32 v[6:7], 0
	v_mov_b64_e32 v[8:9], 0
	v_mov_b64_e32 v[10:11], 0
	v_mov_b64_e32 v[12:13], 0
	v_mov_b64_e32 v[14:15], 0
	v_mov_b64_e32 v[16:17], 0
	v_mov_b64_e32 v[18:19], 0
	v_mov_b64_e32 v[20:21], 0
	v_mov_b64_e32 v[22:23], 0
	v_mov_b64_e32 v[24:25], 0
	v_mov_b64_e32 v[26:27], 0
	v_mov_b64_e32 v[28:29], 0
	v_mov_b64_e32 v[30:31], 0
	v_mov_b64_e32 v[32:33], 0
	v_mov_b64_e32 v[34:35], 0
	v_mov_b64_e32 v[36:37], 0
	v_mov_b64_e32 v[38:39], 0
	v_mov_b64_e32 v[40:41], 0
	v_mov_b64_e32 v[42:43], 0
	v_mov_b64_e32 v[44:45], 0
	v_mov_b64_e32 v[46:47], 0
	v_mov_b64_e32 v[48:49], 0
	v_mov_b64_e32 v[50:51], 0
	v_mov_b64_e32 v[52:53], 0
	v_mov_b64_e32 v[54:55], 0
	v_mov_b64_e32 v[56:57], 0
	v_mov_b64_e32 v[58:59], 0
	v_mov_b64_e32 v[60:61], 0
	v_mov_b64_e32 v[62:63], 0
	v_mov_b64_e32 v[64:65], 0
	v_mov_b64_e32 v[66:67], 0
	v_mov_b64_e32 v[68:69], 0
	v_mov_b64_e32 v[70:71], 0
	v_mov_b64_e32 v[72:73], 0
	v_mov_b64_e32 v[74:75], 0
	v_mov_b64_e32 v[76:77], 0
	v_mov_b64_e32 v[78:79], 0
	v_mov_b64_e32 v[80:81], 0
	v_mov_b64_e32 v[82:83], 0
	v_mov_b64_e32 v[84:85], 0
	v_mov_b64_e32 v[86:87], 0
	v_mov_b64_e32 v[88:89], 0
	v_mov_b64_e32 v[90:91], 0
	v_mov_b64_e32 v[92:93], 0
	v_mov_b64_e32 v[94:95], 0
	v_mov_b64_e32 v[96:97], 0
	v_mov_b64_e32 v[98:99], 0
	v_mov_b64_e32 v[100:101], 0
	v_mov_b64_e32 v[102:103], 0
	v_mov_b64_e32 v[104:105], 0
	v_mov_b64_e32 v[106:107], 0
	v_mov_b64_e32 v[108:109], 0
	v_mov_b64_e32 v[110:111], 0
	v_mov_b64_e32 v[112:113], 0
	v_mov_b64_e32 v[114:115], 0
	v_mov_b64_e32 v[116:117], 0
	v_mov_b64_e32 v[118:119], 0
	v_mov_b64_e32 v[120:121], 0
	v_mov_b64_e32 v[122:123], 0
	v_mov_b64_e32 v[124:125], 0
	v_mov_b64_e32 v[126:127], 0
	s_addc_u32 vcc_hi, s93, 0
	s_mov_b32 s66, -2

; template <class Epi, class Sched, bool ALIGN_EPI = false, bool SP2 = false>
; __device__ __forceinline__ void gemm_phase(PG8_LAS unsigned char* lds, const Gemm g, const Sched& S, const Epi& E) {
;     ...
; #pragma unroll
;         for (int a = 0; a < 2; ++a)
; #pragma unroll
;             for (int b = 0; b < 2; ++b)
; #pragma unroll
;                 for (int m = 0; m < 4; ++m)
; #pragma unroll
;                     for (int n = 0; n < 2; ++n) acc[a][b][m][n] = (f32x4){0.f, 0.f, 0.f, 0.f};
;         cur = nxt; cA = nA; cB = nB; ++ui;
.LBB0_247:
	s_add_u32 s22, s82, 0x100
	v_mov_b64_e32 v[0:1], 0
	v_mov_b64_e32 v[2:3], 0
	v_mov_b64_e32 v[4:5], 0
	v_mov_b64_e32 v[6:7], 0
	v_mov_b64_e32 v[8:9], 0
	v_mov_b64_e32 v[10:11], 0
	v_mov_b64_e32 v[12:13], 0
	v_mov_b64_e32 v[14:15], 0
	v_mov_b64_e32 v[16:17], 0
	v_mov_b64_e32 v[18:19], 0
	v_mov_b64_e32 v[20:21], 0
	v_mov_b64_e32 v[22:23], 0
	v_mov_b64_e32 v[24:25], 0
	v_mov_b64_e32 v[26:27], 0
	v_mov_b64_e32 v[28:29], 0
	v_mov_b64_e32 v[30:31], 0
	v_mov_b64_e32 v[32:33], 0
	v_mov_b64_e32 v[34:35], 0
	v_mov_b64_e32 v[36:37], 0
	v_mov_b64_e32 v[38:39], 0
	v_mov_b64_e32 v[40:41], 0
	v_mov_b64_e32 v[42:43], 0
	v_mov_b64_e32 v[44:45], 0
	v_mov_b64_e32 v[46:47], 0
	v_mov_b64_e32 v[48:49], 0
	v_mov_b64_e32 v[50:51], 0
	v_mov_b64_e32 v[52:53], 0
	v_mov_b64_e32 v[54:55], 0
	v_mov_b64_e32 v[56:57], 0
	v_mov_b64_e32 v[58:59], 0
	v_mov_b64_e32 v[60:61], 0
	v_mov_b64_e32 v[62:63], 0
	v_mov_b64_e32 v[64:65], 0
	v_mov_b64_e32 v[66:67], 0
	v_mov_b64_e32 v[68:69], 0
	v_mov_b64_e32 v[70:71], 0
	v_mov_b64_e32 v[72:73], 0
	v_mov_b64_e32 v[74:75], 0
	v_mov_b64_e32 v[76:77], 0
	v_mov_b64_e32 v[78:79], 0
	v_mov_b64_e32 v[80:81], 0
	v_mov_b64_e32 v[82:83], 0
	v_mov_b64_e32 v[84:85], 0
	v_mov_b64_e32 v[86:87], 0
	v_mov_b64_e32 v[88:89], 0
	v_mov_b64_e32 v[90:91], 0
	v_mov_b64_e32 v[92:93], 0
	v_mov_b64_e32 v[94:95], 0
	v_mov_b64_e32 v[96:97], 0
	v_mov_b64_e32 v[98:99], 0
	v_mov_b64_e32 v[100:101], 0
	v_mov_b64_e32 v[102:103], 0
	v_mov_b64_e32 v[104:105], 0
	v_mov_b64_e32 v[106:107], 0
	v_mov_b64_e32 v[108:109], 0
	v_mov_b64_e32 v[110:111], 0
	v_mov_b64_e32 v[112:113], 0
	v_mov_b64_e32 v[114:115], 0
	v_mov_b64_e32 v[116:117], 0
	v_mov_b64_e32 v[118:119], 0
	v_mov_b64_e32 v[120:121], 0
	v_mov_b64_e32 v[122:123], 0
	v_mov_b64_e32 v[124:125], 0
	v_mov_b64_e32 v[126:127], 0
	s_addc_u32 vcc_lo, s83, 0
	s_mov_b32 s66, -2
	s_waitcnt lgkmcnt(0)

; template <class Epi, class Sched, bool ALIGN_EPI = false, bool SP2 = false>
; __device__ __forceinline__ void gemm_phase(PG8_LAS unsigned char* lds, const Gemm g, const Sched& S, const Epi& E) {
;     ...
; #pragma unroll
;         for (int a = 0; a < 2; ++a)
; #pragma unroll
;             for (int b = 0; b < 2; ++b)
; #pragma unroll
;                 for (int m = 0; m < 4; ++m)
; #pragma unroll
;                     for (int n = 0; n < 2; ++n) acc[a][b][m][n] = (f32x4){0.f, 0.f, 0.f, 0.f};
;         cur = nxt; cA = nA; cB = nB; ++ui;
.LBB0_402:
	s_ashr_i32 s91, s90, 31
	s_lshl_b64 s[12:13], s[90:91], 20
	s_add_u32 s92, s40, s12
	s_addc_u32 s93, s41, s13
	s_and_b64 s[12:13], s[8:9], exec
	s_cselect_b32 s12, s93, s11
	s_cselect_b32 s13, s92, s10
	s_ashr_i32 s89, s88, 31
	s_lshl_b64 s[66:67], s[88:89], 20
	s_add_u32 s82, s84, s66
	s_addc_u32 s83, s85, s67
	s_and_b64 s[66:67], s[8:9], exec
	s_cselect_b32 s47, s83, s97
	s_cselect_b32 s89, s82, s96
	s_add_u32 s10, s10, 0x80080
	s_addc_u32 s11, s11, 0
	s_add_u32 s91, s96, 0x100
	v_mov_b64_e32 v[0:1], 0
	v_mov_b64_e32 v[2:3], 0
	v_mov_b64_e32 v[4:5], 0
	v_mov_b64_e32 v[6:7], 0
	v_mov_b64_e32 v[8:9], 0
	v_mov_b64_e32 v[10:11], 0
	v_mov_b64_e32 v[12:13], 0
	v_mov_b64_e32 v[14:15], 0
	v_mov_b64_e32 v[16:17], 0
	v_mov_b64_e32 v[18:19], 0
	v_mov_b64_e32 v[20:21], 0
	v_mov_b64_e32 v[22:23], 0
	v_mov_b64_e32 v[24:25], 0
	v_mov_b64_e32 v[26:27], 0
	v_mov_b64_e32 v[28:29], 0
	v_mov_b64_e32 v[30:31], 0
	v_mov_b64_e32 v[32:33], 0
	v_mov_b64_e32 v[34:35], 0
	v_mov_b64_e32 v[36:37], 0
	v_mov_b64_e32 v[38:39], 0
	v_mov_b64_e32 v[40:41], 0
	v_mov_b64_e32 v[42:43], 0
	v_mov_b64_e32 v[44:45], 0
	v_mov_b64_e32 v[46:47], 0
	v_mov_b64_e32 v[48:49], 0
	v_mov_b64_e32 v[50:51], 0
	v_mov_b64_e32 v[52:53], 0
	v_mov_b64_e32 v[54:55], 0
	v_mov_b64_e32 v[56:57], 0
	v_mov_b64_e32 v[58:59], 0
	v_mov_b64_e32 v[60:61], 0
	v_mov_b64_e32 v[62:63], 0
	v_mov_b64_e32 v[64:65], 0
	v_mov_b64_e32 v[66:67], 0
	v_mov_b64_e32 v[68:69], 0
	v_mov_b64_e32 v[70:71], 0
	v_mov_b64_e32 v[72:73], 0
	v_mov_b64_e32 v[74:75], 0
	v_mov_b64_e32 v[76:77], 0
	v_mov_b64_e32 v[78:79], 0
	v_mov_b64_e32 v[80:81], 0
	v_mov_b64_e32 v[82:83], 0
	v_mov_b64_e32 v[84:85], 0
	v_mov_b64_e32 v[86:87], 0
	v_mov_b64_e32 v[88:89], 0
	v_mov_b64_e32 v[90:91], 0
	v_mov_b64_e32 v[92:93], 0
	v_mov_b64_e32 v[94:95], 0
	v_mov_b64_e32 v[96:97], 0
	v_mov_b64_e32 v[98:99], 0
	v_mov_b64_e32 v[100:101], 0
	v_mov_b64_e32 v[102:103], 0
	v_mov_b64_e32 v[104:105], 0
	v_mov_b64_e32 v[106:107], 0
	v_mov_b64_e32 v[108:109], 0
	v_mov_b64_e32 v[110:111], 0
	v_mov_b64_e32 v[112:113], 0
	v_mov_b64_e32 v[114:115], 0
	v_mov_b64_e32 v[116:117], 0
	v_mov_b64_e32 v[118:119], 0
	v_mov_b64_e32 v[120:121], 0
	v_mov_b64_e32 v[122:123], 0
	v_mov_b64_e32 v[124:125], 0
	v_mov_b64_e32 v[126:127], 0
	s_addc_u32 s95, s97, 0
	s_mov_b32 s66, -2
	s_waitcnt lgkmcnt(0)

; template <class Epi, class Sched, bool ALIGN_EPI = false, bool SP2 = false>
; __device__ __forceinline__ void gemm_phase(PG8_LAS unsigned char* lds, const Gemm g, const Sched& S, const Epi& E) {
;     ...
; #pragma unroll
;         for (int a = 0; a < 2; ++a)
; #pragma unroll
;             for (int b = 0; b < 2; ++b)
; #pragma unroll
;                 for (int m = 0; m < 4; ++m)
; #pragma unroll
;                     for (int n = 0; n < 2; ++n) acc[a][b][m][n] = (f32x4){0.f, 0.f, 0.f, 0.f};
;         cur = nxt; cA = nA; cB = nB; ++ui;
.LBB0_492:
	s_ashr_i32 s85, s84, 31
	s_lshl_b64 s[12:13], s[84:85], 20
	s_add_u32 s86, s0, s12
	s_addc_u32 s87, s1, s13
	s_and_b64 s[12:13], s[6:7], exec
	s_cselect_b32 s12, s87, s83
	s_cselect_b32 s13, s86, s82
	s_ashr_i32 s47, s46, 31
	s_lshl_b64 s[66:67], s[46:47], 20
	s_add_u32 s88, s40, s66
	s_addc_u32 s89, s41, s67
	s_and_b64 s[66:67], s[6:7], exec
	s_cselect_b32 s47, s89, s95
	s_cselect_b32 s81, s88, s94
	s_add_u32 s92, s82, 0x80080
	s_addc_u32 s93, s83, 0
	s_add_u32 s85, s94, 0x100
	v_mov_b64_e32 v[0:1], 0
	v_mov_b64_e32 v[2:3], 0
	v_mov_b64_e32 v[4:5], 0
	v_mov_b64_e32 v[6:7], 0
	v_mov_b64_e32 v[8:9], 0
	v_mov_b64_e32 v[10:11], 0
	v_mov_b64_e32 v[12:13], 0
	v_mov_b64_e32 v[14:15], 0
	v_mov_b64_e32 v[16:17], 0
	v_mov_b64_e32 v[18:19], 0
	v_mov_b64_e32 v[20:21], 0
	v_mov_b64_e32 v[22:23], 0
	v_mov_b64_e32 v[24:25], 0
	v_mov_b64_e32 v[26:27], 0
	v_mov_b64_e32 v[28:29], 0
	v_mov_b64_e32 v[30:31], 0
	v_mov_b64_e32 v[32:33], 0
	v_mov_b64_e32 v[34:35], 0
	v_mov_b64_e32 v[36:37], 0
	v_mov_b64_e32 v[38:39], 0
	v_mov_b64_e32 v[40:41], 0
	v_mov_b64_e32 v[42:43], 0
	v_mov_b64_e32 v[44:45], 0
	v_mov_b64_e32 v[46:47], 0
	v_mov_b64_e32 v[48:49], 0
	v_mov_b64_e32 v[50:51], 0
	v_mov_b64_e32 v[52:53], 0
	v_mov_b64_e32 v[54:55], 0
	v_mov_b64_e32 v[56:57], 0
	v_mov_b64_e32 v[58:59], 0
	v_mov_b64_e32 v[60:61], 0
	v_mov_b64_e32 v[62:63], 0
	v_mov_b64_e32 v[64:65], 0
	v_mov_b64_e32 v[66:67], 0
	v_mov_b64_e32 v[68:69], 0
	v_mov_b64_e32 v[70:71], 0
	v_mov_b64_e32 v[72:73], 0
	v_mov_b64_e32 v[74:75], 0
	v_mov_b64_e32 v[76:77], 0
	v_mov_b64_e32 v[78:79], 0
	v_mov_b64_e32 v[80:81], 0
	v_mov_b64_e32 v[82:83], 0
	v_mov_b64_e32 v[84:85], 0
	v_mov_b64_e32 v[86:87], 0
	v_mov_b64_e32 v[88:89], 0
	v_mov_b64_e32 v[90:91], 0
	v_mov_b64_e32 v[92:93], 0
	v_mov_b64_e32 v[94:95], 0
	v_mov_b64_e32 v[96:97], 0
	v_mov_b64_e32 v[98:99], 0
	v_mov_b64_e32 v[100:101], 0
	v_mov_b64_e32 v[102:103], 0
	v_mov_b64_e32 v[104:105], 0
	v_mov_b64_e32 v[106:107], 0
	v_mov_b64_e32 v[108:109], 0
	v_mov_b64_e32 v[110:111], 0
	v_mov_b64_e32 v[112:113], 0
	v_mov_b64_e32 v[114:115], 0
	v_mov_b64_e32 v[116:117], 0
	v_mov_b64_e32 v[118:119], 0
	v_mov_b64_e32 v[120:121], 0
	v_mov_b64_e32 v[122:123], 0
	v_mov_b64_e32 v[124:125], 0
	v_mov_b64_e32 v[126:127], 0
	s_addc_u32 s91, s95, 0
	s_mov_b32 s66, -2

; template <class Epi, class Sched, bool ALIGN_EPI = false, bool SP2 = false>
; __device__ __forceinline__ void gemm_phase(PG8_LAS unsigned char* lds, const Gemm g, const Sched& S, const Epi& E) {
;     ...
; #pragma unroll
;         for (int a = 0; a < 2; ++a)
; #pragma unroll
;             for (int b = 0; b < 2; ++b)
; #pragma unroll
;                 for (int m = 0; m < 4; ++m)
; #pragma unroll
;                     for (int n = 0; n < 2; ++n) acc[a][b][m][n] = (f32x4){0.f, 0.f, 0.f, 0.f};
;         cur = nxt; cA = nA; cB = nB; ++ui;
.LBB0_780:
	s_ashr_i32 s29, s28, 31
	s_lshl_b64 s[12:13], s[28:29], 19
	s_add_u32 s30, s38, s12
	s_addc_u32 s31, s39, s13
	s_and_b64 s[12:13], s[6:7], exec
	s_cselect_b32 s12, s31, s47
	s_cselect_b32 s13, s30, s46
	s_ashr_i32 s21, s20, 31
	s_lshl_b64 s[42:43], s[20:21], 19
	v_readlane_b32 s50, v252, 4
	v_readlane_b32 s51, v252, 5
	s_add_u32 s42, s50, s42
	s_addc_u32 s43, s51, s43
	s_and_b64 s[50:51], s[6:7], exec
	s_cselect_b32 s21, s43, s49
	s_cselect_b32 s29, s42, s48
	s_add_u32 s46, s46, 0x40080
	s_addc_u32 s47, s47, 0
	s_add_u32 s71, s48, 0x100
	v_mov_b64_e32 v[0:1], 0
	v_mov_b64_e32 v[2:3], 0
	v_mov_b64_e32 v[4:5], 0
	v_mov_b64_e32 v[6:7], 0
	v_mov_b64_e32 v[8:9], 0
	v_mov_b64_e32 v[10:11], 0
	v_mov_b64_e32 v[12:13], 0
	v_mov_b64_e32 v[14:15], 0
	v_mov_b64_e32 v[16:17], 0
	v_mov_b64_e32 v[18:19], 0
	v_mov_b64_e32 v[20:21], 0
	v_mov_b64_e32 v[22:23], 0
	v_mov_b64_e32 v[24:25], 0
	v_mov_b64_e32 v[26:27], 0
	v_mov_b64_e32 v[28:29], 0
	v_mov_b64_e32 v[30:31], 0
	v_mov_b64_e32 v[32:33], 0
	v_mov_b64_e32 v[34:35], 0
	v_mov_b64_e32 v[36:37], 0
	v_mov_b64_e32 v[38:39], 0
	v_mov_b64_e32 v[40:41], 0
	v_mov_b64_e32 v[42:43], 0
	v_mov_b64_e32 v[44:45], 0
	v_mov_b64_e32 v[46:47], 0
	v_mov_b64_e32 v[48:49], 0
	v_mov_b64_e32 v[50:51], 0
	v_mov_b64_e32 v[52:53], 0
	v_mov_b64_e32 v[54:55], 0
	v_mov_b64_e32 v[56:57], 0
	v_mov_b64_e32 v[58:59], 0
	v_mov_b64_e32 v[60:61], 0
	v_mov_b64_e32 v[62:63], 0
	v_mov_b64_e32 v[64:65], 0
	v_mov_b64_e32 v[66:67], 0
	v_mov_b64_e32 v[68:69], 0
	v_mov_b64_e32 v[70:71], 0
	v_mov_b64_e32 v[72:73], 0
	v_mov_b64_e32 v[74:75], 0
	v_mov_b64_e32 v[76:77], 0
	v_mov_b64_e32 v[78:79], 0
	v_mov_b64_e32 v[80:81], 0
	v_mov_b64_e32 v[82:83], 0
	v_mov_b64_e32 v[84:85], 0
	v_mov_b64_e32 v[86:87], 0
	v_mov_b64_e32 v[88:89], 0
	v_mov_b64_e32 v[90:91], 0
	v_mov_b64_e32 v[92:93], 0
	v_mov_b64_e32 v[94:95], 0
	v_mov_b64_e32 v[96:97], 0
	v_mov_b64_e32 v[98:99], 0
	v_mov_b64_e32 v[100:101], 0
	v_mov_b64_e32 v[102:103], 0
	v_mov_b64_e32 v[104:105], 0
	v_mov_b64_e32 v[106:107], 0
	v_mov_b64_e32 v[108:109], 0
	v_mov_b64_e32 v[110:111], 0
	v_mov_b64_e32 v[112:113], 0
	v_mov_b64_e32 v[114:115], 0
	v_mov_b64_e32 v[116:117], 0
	v_mov_b64_e32 v[118:119], 0
	v_mov_b64_e32 v[120:121], 0
	v_mov_b64_e32 v[122:123], 0
	v_mov_b64_e32 v[124:125], 0
	v_mov_b64_e32 v[126:127], 0
	s_addc_u32 s72, s49, 0
	s_mov_b32 s66, -2

; template <class Epi, class Sched, bool ALIGN_EPI = false, bool SP2 = false>
; __device__ __forceinline__ void gemm_phase(PG8_LAS unsigned char* lds, const Gemm g, const Sched& S, const Epi& E) {
;     ...
; #pragma unroll
;         for (int a = 0; a < 2; ++a)
; #pragma unroll
;             for (int b = 0; b < 2; ++b)
; #pragma unroll
;                 for (int m = 0; m < 4; ++m)
; #pragma unroll
;                     for (int n = 0; n < 2; ++n) acc[a][b][m][n] = (f32x4){0.f, 0.f, 0.f, 0.f};
;         cur = nxt; cA = nA; cB = nB; ++ui;
.LBB0_800:
	s_ashr_i32 s29, s28, 31
	s_lshl_b64 s[12:13], s[28:29], 19
	s_add_u32 s30, s8, s12
	s_addc_u32 s31, s9, s13
	s_and_b64 s[12:13], s[6:7], exec
	s_cselect_b32 s12, s31, s47
	s_cselect_b32 s13, s30, s46
	s_ashr_i32 s21, s20, 31
	s_lshl_b64 s[42:43], s[20:21], 19
	v_readlane_b32 s50, v252, 6
	v_readlane_b32 s51, v252, 7
	s_add_u32 s42, s50, s42
	s_addc_u32 s43, s51, s43
	s_and_b64 s[50:51], s[6:7], exec
	s_cselect_b32 s21, s43, s49
	s_cselect_b32 s29, s42, s48
	s_add_u32 s46, s46, 0x40080
	s_addc_u32 s47, s47, 0
	s_add_u32 s71, s48, 0x100
	v_mov_b64_e32 v[0:1], 0
	v_mov_b64_e32 v[2:3], 0
	v_mov_b64_e32 v[4:5], 0
	v_mov_b64_e32 v[6:7], 0
	v_mov_b64_e32 v[8:9], 0
	v_mov_b64_e32 v[10:11], 0
	v_mov_b64_e32 v[12:13], 0
	v_mov_b64_e32 v[14:15], 0
	v_mov_b64_e32 v[16:17], 0
	v_mov_b64_e32 v[18:19], 0
	v_mov_b64_e32 v[20:21], 0
	v_mov_b64_e32 v[22:23], 0
	v_mov_b64_e32 v[24:25], 0
	v_mov_b64_e32 v[26:27], 0
	v_mov_b64_e32 v[28:29], 0
	v_mov_b64_e32 v[30:31], 0
	v_mov_b64_e32 v[32:33], 0
	v_mov_b64_e32 v[34:35], 0
	v_mov_b64_e32 v[36:37], 0
	v_mov_b64_e32 v[38:39], 0
	v_mov_b64_e32 v[40:41], 0
	v_mov_b64_e32 v[42:43], 0
	v_mov_b64_e32 v[44:45], 0
	v_mov_b64_e32 v[46:47], 0
	v_mov_b64_e32 v[48:49], 0
	v_mov_b64_e32 v[50:51], 0
	v_mov_b64_e32 v[52:53], 0
	v_mov_b64_e32 v[54:55], 0
	v_mov_b64_e32 v[56:57], 0
	v_mov_b64_e32 v[58:59], 0
	v_mov_b64_e32 v[60:61], 0
	v_mov_b64_e32 v[62:63], 0
	v_mov_b64_e32 v[64:65], 0
	v_mov_b64_e32 v[66:67], 0
	v_mov_b64_e32 v[68:69], 0
	v_mov_b64_e32 v[70:71], 0
	v_mov_b64_e32 v[72:73], 0
	v_mov_b64_e32 v[74:75], 0
	v_mov_b64_e32 v[76:77], 0
	v_mov_b64_e32 v[78:79], 0
	v_mov_b64_e32 v[80:81], 0
	v_mov_b64_e32 v[82:83], 0
	v_mov_b64_e32 v[84:85], 0
	v_mov_b64_e32 v[86:87], 0
	v_mov_b64_e32 v[88:89], 0
	v_mov_b64_e32 v[90:91], 0
	v_mov_b64_e32 v[92:93], 0
	v_mov_b64_e32 v[94:95], 0
	v_mov_b64_e32 v[96:97], 0
	v_mov_b64_e32 v[98:99], 0
	v_mov_b64_e32 v[100:101], 0
	v_mov_b64_e32 v[102:103], 0
	v_mov_b64_e32 v[104:105], 0
	v_mov_b64_e32 v[106:107], 0
	v_mov_b64_e32 v[108:109], 0
	v_mov_b64_e32 v[110:111], 0
	v_mov_b64_e32 v[112:113], 0
	v_mov_b64_e32 v[114:115], 0
	v_mov_b64_e32 v[116:117], 0
	v_mov_b64_e32 v[118:119], 0
	v_mov_b64_e32 v[120:121], 0
	v_mov_b64_e32 v[122:123], 0
	v_mov_b64_e32 v[124:125], 0
	v_mov_b64_e32 v[126:127], 0
	s_addc_u32 s72, s49, 0
	s_mov_b32 s66, -2

; template <class Epi, class Sched, bool ALIGN_EPI = false, bool SP2 = false>
; __device__ __forceinline__ void gemm_phase(PG8_LAS unsigned char* lds, const Gemm g, const Sched& S, const Epi& E) {
;     ...
; #pragma unroll
;         for (int a = 0; a < 2; ++a)
; #pragma unroll
;             for (int b = 0; b < 2; ++b)
; #pragma unroll
;                 for (int m = 0; m < 4; ++m)
; #pragma unroll
;                     for (int n = 0; n < 2; ++n) acc[a][b][m][n] = (f32x4){0.f, 0.f, 0.f, 0.f};
;         cur = nxt; cA = nA; cB = nB; ++ui;
.LBB0_875:
	s_ashr_i32 s31, s30, 31
	s_lshl_b64 s[12:13], s[30:31], 20
	s_add_u32 s42, s36, s12
	s_addc_u32 s43, s37, s13
	s_and_b64 s[12:13], s[8:9], exec
	s_cselect_b32 s11, s43, s47
	s_cselect_b32 s12, s42, s46
	s_ashr_i32 s29, s28, 31
	s_lshl_b64 s[44:45], s[28:29], 20
	v_readlane_b32 s50, v252, 8
	v_readlane_b32 s51, v252, 9
	s_add_u32 s44, s50, s44
	s_addc_u32 s45, s51, s45
	s_and_b64 s[50:51], s[8:9], exec
	s_cselect_b32 s13, s45, s49
	s_cselect_b32 s29, s44, s48
	s_add_u32 s31, s48, 0x100
	v_mov_b64_e32 v[0:1], 0
	v_mov_b64_e32 v[2:3], 0
	v_mov_b64_e32 v[4:5], 0
	v_mov_b64_e32 v[6:7], 0
	v_mov_b64_e32 v[8:9], 0
	v_mov_b64_e32 v[10:11], 0
	v_mov_b64_e32 v[12:13], 0
	v_mov_b64_e32 v[14:15], 0
	v_mov_b64_e32 v[16:17], 0
	v_mov_b64_e32 v[18:19], 0
	v_mov_b64_e32 v[20:21], 0
	v_mov_b64_e32 v[22:23], 0
	v_mov_b64_e32 v[24:25], 0
	v_mov_b64_e32 v[26:27], 0
	v_mov_b64_e32 v[28:29], 0
	v_mov_b64_e32 v[30:31], 0
	v_mov_b64_e32 v[32:33], 0
	v_mov_b64_e32 v[34:35], 0
	v_mov_b64_e32 v[36:37], 0
	v_mov_b64_e32 v[38:39], 0
	v_mov_b64_e32 v[40:41], 0
	v_mov_b64_e32 v[42:43], 0
	v_mov_b64_e32 v[44:45], 0
	v_mov_b64_e32 v[46:47], 0
	v_mov_b64_e32 v[48:49], 0
	v_mov_b64_e32 v[50:51], 0
	v_mov_b64_e32 v[52:53], 0
	v_mov_b64_e32 v[54:55], 0
	v_mov_b64_e32 v[56:57], 0
	v_mov_b64_e32 v[58:59], 0
	v_mov_b64_e32 v[60:61], 0
	v_mov_b64_e32 v[62:63], 0
	v_mov_b64_e32 v[64:65], 0
	v_mov_b64_e32 v[66:67], 0
	v_mov_b64_e32 v[68:69], 0
	v_mov_b64_e32 v[70:71], 0
	v_mov_b64_e32 v[72:73], 0
	v_mov_b64_e32 v[74:75], 0
	v_mov_b64_e32 v[76:77], 0
	v_mov_b64_e32 v[78:79], 0
	v_mov_b64_e32 v[80:81], 0
	v_mov_b64_e32 v[82:83], 0
	v_mov_b64_e32 v[84:85], 0
	v_mov_b64_e32 v[86:87], 0
	v_mov_b64_e32 v[88:89], 0
	v_mov_b64_e32 v[90:91], 0
	v_mov_b64_e32 v[92:93], 0
	v_mov_b64_e32 v[94:95], 0
	v_mov_b64_e32 v[96:97], 0
	v_mov_b64_e32 v[98:99], 0
	v_mov_b64_e32 v[100:101], 0
	v_mov_b64_e32 v[102:103], 0
	v_mov_b64_e32 v[104:105], 0
	v_mov_b64_e32 v[106:107], 0
	v_mov_b64_e32 v[108:109], 0
	v_mov_b64_e32 v[110:111], 0
	v_mov_b64_e32 v[112:113], 0
	v_mov_b64_e32 v[114:115], 0
	v_mov_b64_e32 v[116:117], 0
	v_mov_b64_e32 v[118:119], 0
	v_mov_b64_e32 v[120:121], 0
	v_mov_b64_e32 v[122:123], 0
	v_mov_b64_e32 v[124:125], 0
	v_mov_b64_e32 v[126:127], 0
	s_addc_u32 s72, s49, 0
	s_mov_b32 s66, -2
	s_waitcnt lgkmcnt(0)

; template <class Epi, class Sched, bool ALIGN_EPI = false, bool SP2 = false>
; __device__ __forceinline__ void gemm_phase(PG8_LAS unsigned char* lds, const Gemm g, const Sched& S, const Epi& E) {
;     ...
; #pragma unroll
;         for (int a = 0; a < 2; ++a)
; #pragma unroll
;             for (int b = 0; b < 2; ++b)
; #pragma unroll
;                 for (int m = 0; m < 4; ++m)
; #pragma unroll
;                     for (int n = 0; n < 2; ++n) acc[a][b][m][n] = (f32x4){0.f, 0.f, 0.f, 0.f};
;         cur = nxt; cA = nA; cB = nB; ++ui;
.LBB0_1024:
	s_ashr_i32 s19, s18, 31
	s_lshl_b64 s[12:13], s[18:19], 20
	s_add_u32 s20, s40, s12
	s_addc_u32 s21, s41, s13
	s_and_b64 s[12:13], s[6:7], exec
	s_cselect_b32 s12, s21, s29
	s_cselect_b32 s13, s20, s28
	s_ashr_i32 s1, s0, 31
	s_lshl_b64 s[24:25], s[0:1], 20
	s_add_u32 s24, s64, s24
	s_addc_u32 s25, s65, s25
	s_and_b64 s[36:37], s[6:7], exec
	s_cselect_b32 s1, s25, s31
	s_cselect_b32 s19, s24, s30
	s_add_u32 s28, s28, 0x80080
	s_addc_u32 s29, s29, 0
	s_add_u32 s47, s30, 0x100
	v_mov_b64_e32 v[0:1], 0
	v_mov_b64_e32 v[2:3], 0
	v_mov_b64_e32 v[4:5], 0
	v_mov_b64_e32 v[6:7], 0
	v_mov_b64_e32 v[8:9], 0
	v_mov_b64_e32 v[10:11], 0
	v_mov_b64_e32 v[12:13], 0
	v_mov_b64_e32 v[14:15], 0
	v_mov_b64_e32 v[16:17], 0
	v_mov_b64_e32 v[18:19], 0
	v_mov_b64_e32 v[20:21], 0
	v_mov_b64_e32 v[22:23], 0
	v_mov_b64_e32 v[24:25], 0
	v_mov_b64_e32 v[26:27], 0
	v_mov_b64_e32 v[28:29], 0
	v_mov_b64_e32 v[30:31], 0
	v_mov_b64_e32 v[32:33], 0
	v_mov_b64_e32 v[34:35], 0
	v_mov_b64_e32 v[36:37], 0
	v_mov_b64_e32 v[38:39], 0
	v_mov_b64_e32 v[40:41], 0
	v_mov_b64_e32 v[42:43], 0
	v_mov_b64_e32 v[44:45], 0
	v_mov_b64_e32 v[46:47], 0
	v_mov_b64_e32 v[48:49], 0
	v_mov_b64_e32 v[50:51], 0
	v_mov_b64_e32 v[52:53], 0
	v_mov_b64_e32 v[54:55], 0
	v_mov_b64_e32 v[56:57], 0
	v_mov_b64_e32 v[58:59], 0
	v_mov_b64_e32 v[60:61], 0
	v_mov_b64_e32 v[62:63], 0
	v_mov_b64_e32 v[64:65], 0
	v_mov_b64_e32 v[66:67], 0
	v_mov_b64_e32 v[68:69], 0
	v_mov_b64_e32 v[70:71], 0
	v_mov_b64_e32 v[72:73], 0
	v_mov_b64_e32 v[74:75], 0
	v_mov_b64_e32 v[76:77], 0
	v_mov_b64_e32 v[78:79], 0
	v_mov_b64_e32 v[80:81], 0
	v_mov_b64_e32 v[82:83], 0
	v_mov_b64_e32 v[84:85], 0
	v_mov_b64_e32 v[86:87], 0
	v_mov_b64_e32 v[88:89], 0
	v_mov_b64_e32 v[90:91], 0
	v_mov_b64_e32 v[92:93], 0
	v_mov_b64_e32 v[94:95], 0
	v_mov_b64_e32 v[96:97], 0
	v_mov_b64_e32 v[98:99], 0
	v_mov_b64_e32 v[100:101], 0
	v_mov_b64_e32 v[102:103], 0
	v_mov_b64_e32 v[104:105], 0
	v_mov_b64_e32 v[106:107], 0
	v_mov_b64_e32 v[108:109], 0
	v_mov_b64_e32 v[110:111], 0
	v_mov_b64_e32 v[112:113], 0
	v_mov_b64_e32 v[114:115], 0
	v_mov_b64_e32 v[116:117], 0
	v_mov_b64_e32 v[118:119], 0
	v_mov_b64_e32 v[120:121], 0
	v_mov_b64_e32 v[122:123], 0
	v_mov_b64_e32 v[124:125], 0
	v_mov_b64_e32 v[126:127], 0
	s_addc_u32 s48, s31, 0
	s_mov_b32 s49, -2

; template <class Epi, class Sched, bool ALIGN_EPI = false, bool SP2 = false>
; __device__ __forceinline__ void gemm_phase(PG8_LAS unsigned char* lds, const Gemm g, const Sched& S, const Epi& E) {
;     ...
;     f32x4 acc[2][2][4][2];
; #pragma unroll
;     for (int a = 0; a < 2; ++a)
; #pragma unroll
;         for (int b = 0; b < 2; ++b)
; #pragma unroll
;             for (int m = 0; m < 4; ++m)
; #pragma unroll
;                 for (int n = 0; n < 2; ++n) acc[a][b][m][n] = (f32x4){0.f, 0.f, 0.f, 0.f};
.LBB0_1107:
	s_add_u32 s13, s30, 0x100
	v_mov_b64_e32 v[0:1], 0
	v_mov_b64_e32 v[2:3], 0
	v_mov_b64_e32 v[4:5], 0
	v_mov_b64_e32 v[6:7], 0
	v_mov_b64_e32 v[8:9], 0
	v_mov_b64_e32 v[10:11], 0
	v_mov_b64_e32 v[12:13], 0
	v_mov_b64_e32 v[14:15], 0
	v_mov_b64_e32 v[16:17], 0
	v_mov_b64_e32 v[18:19], 0
	v_mov_b64_e32 v[20:21], 0
	v_mov_b64_e32 v[22:23], 0
	v_mov_b64_e32 v[24:25], 0
	v_mov_b64_e32 v[26:27], 0
	v_mov_b64_e32 v[28:29], 0
	v_mov_b64_e32 v[30:31], 0
	v_mov_b64_e32 v[32:33], 0
	v_mov_b64_e32 v[34:35], 0
	v_mov_b64_e32 v[36:37], 0
	v_mov_b64_e32 v[38:39], 0
	v_mov_b64_e32 v[40:41], 0
	v_mov_b64_e32 v[42:43], 0
	v_mov_b64_e32 v[44:45], 0
	v_mov_b64_e32 v[46:47], 0
	v_mov_b64_e32 v[48:49], 0
	v_mov_b64_e32 v[50:51], 0
	v_mov_b64_e32 v[52:53], 0
	v_mov_b64_e32 v[54:55], 0
	v_mov_b64_e32 v[56:57], 0
	v_mov_b64_e32 v[58:59], 0
	v_mov_b64_e32 v[60:61], 0
	v_mov_b64_e32 v[62:63], 0
	v_mov_b64_e32 v[64:65], 0
	v_mov_b64_e32 v[66:67], 0
	v_mov_b64_e32 v[68:69], 0
	v_mov_b64_e32 v[70:71], 0
	v_mov_b64_e32 v[72:73], 0
	v_mov_b64_e32 v[74:75], 0
	v_mov_b64_e32 v[76:77], 0
	v_mov_b64_e32 v[78:79], 0
	v_mov_b64_e32 v[80:81], 0
	v_mov_b64_e32 v[82:83], 0
	v_mov_b64_e32 v[84:85], 0
	v_mov_b64_e32 v[86:87], 0
	v_mov_b64_e32 v[88:89], 0
	v_mov_b64_e32 v[90:91], 0
	v_mov_b64_e32 v[92:93], 0
	v_mov_b64_e32 v[94:95], 0
	v_mov_b64_e32 v[96:97], 0
	v_mov_b64_e32 v[98:99], 0
	v_mov_b64_e32 v[100:101], 0
	v_mov_b64_e32 v[102:103], 0
	v_mov_b64_e32 v[104:105], 0
	v_mov_b64_e32 v[106:107], 0
	v_mov_b64_e32 v[108:109], 0
	v_mov_b64_e32 v[110:111], 0
	v_mov_b64_e32 v[112:113], 0
	v_mov_b64_e32 v[114:115], 0
	v_mov_b64_e32 v[116:117], 0
	v_mov_b64_e32 v[118:119], 0
	v_mov_b64_e32 v[120:121], 0
	v_mov_b64_e32 v[122:123], 0
	v_mov_b64_e32 v[124:125], 0
	v_mov_b64_e32 v[126:127], 0
	s_addc_u32 s49, s31, 0
	s_mov_b32 s50, -2
	s_waitcnt lgkmcnt(0)

; #define PG8_STAGE(bufoff, gbase, voff) do { _Pragma("unroll") for (int _i = 0; _i < 2; ++_i) \
;         __builtin_amdgcn_global_load_lds((const unsigned*)((const char*)(gbase) + (voff)[_i]), (PG8_LAS unsigned*)(lds + (bufoff) + ldsw + _i * 8192), 16, 0, 0); } while (0)
; #define PG8_LDA(dst, b, h) do { _Pragma("unroll") for (int m = 0; m < 4; ++m) _Pragma("unroll") for (int k = 0; k < 2; ++k) dst[m][k] = *(const PG8_LAS bf16x8*)(lds + PG8_SA(b, h) + aoff + m * 2048 + k * 1024); } while (0)
; #define PG8_LDB(dst, b, h) do { _Pragma("unroll") for (int n = 0; n < 2; ++n) _Pragma("unroll") for (int k = 0; k < 2; ++k) dst[n][k] = *(const PG8_LAS bf16x8*)(lds + PG8_SB(b, h) + boff + n * 2048 + k * 1024); } while (0)
; #define PG8_MMA(ai, bj, At, Bt) do { __builtin_amdgcn_s_setprio(1); _Pragma("unroll") for (int m = 0; m < 4; ++m) _Pragma("unroll") for (int n = 0; n < 2; ++n) _Pragma("unroll") for (int k = 0; k < 2; ++k) \
;         acc[ai][bj][m][n] = __builtin_amdgcn_mfma_f32_16x16x32_bf16(Bt[n][k], At[m][k], acc[ai][bj][m][n], 0, 0, 0); __builtin_amdgcn_s_setprio(0); } while (0)
; #define PG8_WAIT_V(n) asm volatile("s_waitcnt vmcnt(" #n ")" ::: "memory")
; #define PG8_WAIT_L(n) asm volatile("s_waitcnt lgkmcnt(" #n ")" ::: "memory")
; #define PG8_BAR __builtin_amdgcn_s_barrier()
; #define PG8_SCHED __builtin_amdgcn_sched_barrier(0)
; template <class Epi, class Sched, bool ALIGN_EPI = false, bool SP2 = false>
; __device__ __forceinline__ void gemm_phase(PG8_LAS unsigned char* lds, const Gemm g, const Sched& S, const Epi& E) {
;     ...
;             if constexpr (SP2) {
;             PG8_LDB(B0, 0, 0); PG8_LDB(B1, 0, 1); PG8_SCHED; PG8_LDA(At, 0, 0); PG8_STAGE(PG8_SA(1, 1), a1 + hstep, voffA);
;             PG8_WAIT_V(8); PG8_WAIT_L(0); PG8_BAR; PG8_MMA(0, 0, At, B0); PG8_MMA(0, 1, At, B1); PG8_BAR; PG8_SCHED;
;             PG8_LDA(At, 0, 1); PG8_STAGE(PG8_SB(0, 0), b2, voffB); PG8_STAGE(PG8_SB(0, 1), b2 + hstep, voffB); PG8_STAGE(PG8_SA(0, 0), a2, voffA);
;             PG8_WAIT_V(8); PG8_WAIT_L(0); PG8_BAR; PG8_MMA(1, 0, At, B0); PG8_MMA(1, 1, At, B1); PG8_BAR; PG8_SCHED;
.LBB0_1205:
	v_add_u32_e32 v147, s40, v145
	ds_read_b128 v[148:151], v147
	ds_read_b128 v[152:155], v147 offset:1024
	ds_read_b128 v[156:159], v147 offset:2048
	ds_read_b128 v[160:163], v147 offset:3072
	v_add_u32_e32 v147, s41, v145
	s_add_u32 s20, s10, s18
	ds_read_b128 v[164:167], v147
	ds_read_b128 v[168:171], v147 offset:1024
	ds_read_b128 v[172:175], v147 offset:2048
	ds_read_b128 v[176:179], v147 offset:3072
	s_addc_u32 s21, s11, s19
	s_add_u32 s20, s20, 0x100
	s_addc_u32 s21, s21, 0
	s_add_u32 s46, s15, s18
	s_addc_u32 s47, s44, s19
	s_cmpk_eq_i32 s18, 0x2b00
	s_cselect_b32 s23, s17, s21
	s_cselect_b32 s22, s16, s20
	s_cselect_b32 s21, s7, s47
	s_cselect_b32 s20, s6, s46
	v_lshl_add_u64 v[180:181], v[140:141], 0, s[18:19]
	s_add_i32 m0, s28, 0xc000
	ds_read_b128 v[184:187], v146
	ds_read_b128 v[188:191], v146 offset:1024
	ds_read_b128 v[192:195], v146 offset:2048
	ds_read_b128 v[196:199], v146 offset:3072
	ds_read_b128 v[200:203], v146 offset:4096
	ds_read_b128 v[204:207], v146 offset:5120
	ds_read_b128 v[208:211], v146 offset:6144
	ds_read_b128 v[212:215], v146 offset:7168
	global_load_lds_dwordx4 v[180:181], off
	v_lshl_add_u64 v[180:181], v[142:143], 0, s[18:19]
	s_add_i32 m0, s28, 0xe000
	s_nop 0
	global_load_lds_dwordx4 v[180:181], off
	s_waitcnt vmcnt(8)
	s_waitcnt lgkmcnt(0)
	s_setprio 1
	s_barrier
	v_mfma_f32_16x16x32_bf16 v[124:127], v[148:151], v[184:187], v[124:127]
	v_mfma_f32_16x16x32_bf16 v[120:123], v[156:159], v[184:187], v[120:123]
	v_mfma_f32_16x16x32_bf16 v[108:111], v[148:151], v[192:195], v[108:111]
	v_mfma_f32_16x16x32_bf16 v[104:107], v[156:159], v[192:195], v[104:107]
	v_mfma_f32_16x16x32_bf16 v[96:99], v[148:151], v[200:203], v[96:99]
	v_mfma_f32_16x16x32_bf16 v[88:91], v[156:159], v[200:203], v[88:91]
	v_mfma_f32_16x16x32_bf16 v[80:83], v[148:151], v[208:211], v[80:83]
	v_mfma_f32_16x16x32_bf16 v[72:75], v[156:159], v[208:211], v[72:75]
	v_mfma_f32_16x16x32_bf16 v[124:127], v[152:155], v[188:191], v[124:127]
	v_mfma_f32_16x16x32_bf16 v[120:123], v[160:163], v[188:191], v[120:123]
	v_mfma_f32_16x16x32_bf16 v[108:111], v[152:155], v[196:199], v[108:111]
	v_mfma_f32_16x16x32_bf16 v[104:107], v[160:163], v[196:199], v[104:107]
	v_mfma_f32_16x16x32_bf16 v[96:99], v[152:155], v[204:207], v[96:99]
	v_mfma_f32_16x16x32_bf16 v[88:91], v[160:163], v[204:207], v[88:91]
	v_mfma_f32_16x16x32_bf16 v[80:83], v[152:155], v[212:215], v[80:83]
	v_mfma_f32_16x16x32_bf16 v[72:75], v[160:163], v[212:215], v[72:75]
	v_mfma_f32_16x16x32_bf16 v[116:119], v[164:167], v[184:187], v[116:119]
	v_mfma_f32_16x16x32_bf16 v[112:115], v[172:175], v[184:187], v[112:115]
	v_mfma_f32_16x16x32_bf16 v[100:103], v[164:167], v[192:195], v[100:103]
	v_mfma_f32_16x16x32_bf16 v[92:95], v[172:175], v[192:195], v[92:95]
	v_mfma_f32_16x16x32_bf16 v[84:87], v[164:167], v[200:203], v[84:87]
	v_mfma_f32_16x16x32_bf16 v[76:79], v[172:175], v[200:203], v[76:79]
	v_mfma_f32_16x16x32_bf16 v[68:71], v[164:167], v[208:211], v[68:71]
	v_mfma_f32_16x16x32_bf16 v[64:67], v[172:175], v[208:211], v[64:67]
	v_mfma_f32_16x16x32_bf16 v[116:119], v[168:171], v[188:191], v[116:119]
	v_mfma_f32_16x16x32_bf16 v[112:115], v[176:179], v[188:191], v[112:115]
	v_mfma_f32_16x16x32_bf16 v[100:103], v[168:171], v[196:199], v[100:103]
	v_mfma_f32_16x16x32_bf16 v[92:95], v[176:179], v[196:199], v[92:95]
	v_mfma_f32_16x16x32_bf16 v[84:87], v[168:171], v[204:207], v[84:87]
	v_mfma_f32_16x16x32_bf16 v[76:79], v[176:179], v[204:207], v[76:79]
	v_mfma_f32_16x16x32_bf16 v[68:71], v[168:171], v[212:215], v[68:71]
	v_mfma_f32_16x16x32_bf16 v[64:67], v[176:179], v[212:215], v[64:67]
	s_barrier
	s_setprio 0
	s_add_i32 s46, s40, s27
	v_lshl_add_u64 v[180:181], s[20:21], 0, v[130:131]
	s_mov_b32 m0, s46
	ds_read_b128 v[184:187], v146 offset:16384
	ds_read_b128 v[188:191], v146 offset:17408
	ds_read_b128 v[192:195], v146 offset:18432
	ds_read_b128 v[196:199], v146 offset:19456
	ds_read_b128 v[200:203], v146 offset:20480
	ds_read_b128 v[204:207], v146 offset:21504
	ds_read_b128 v[208:211], v146 offset:22528
	ds_read_b128 v[212:215], v146 offset:23552
	global_load_lds_dwordx4 v[180:181], off
	s_add_i32 m0, s46, 0x2000
	s_add_u32 s46, s20, 0x160000
	v_lshl_add_u64 v[216:217], s[20:21], 0, v[128:129]
	s_addc_u32 s47, s21, 0
	s_add_i32 s48, s41, s27
	global_load_lds_dwordx4 v[216:217], off
	v_lshl_add_u64 v[218:219], s[46:47], 0, v[130:131]
	s_mov_b32 m0, s48
	v_lshl_add_u64 v[220:221], s[22:23], 0, v[128:129]
	global_load_lds_dwordx4 v[218:219], off
	v_lshl_add_u64 v[218:219], s[46:47], 0, v[128:129]
	s_add_i32 m0, s48, 0x2000
	s_nop 0
	global_load_lds_dwordx4 v[218:219], off
	v_lshl_add_u64 v[218:219], s[22:23], 0, v[130:131]
	s_mov_b32 m0, s28
	s_nop 0
	global_load_lds_dwordx4 v[218:219], off
	s_mov_b32 m0, s29
	s_nop 0
	global_load_lds_dwordx4 v[220:221], off
	s_waitcnt vmcnt(8)
	s_waitcnt lgkmcnt(0)
	s_setprio 1
	s_barrier
; #define PG8_STAGE(bufoff, gbase, voff) do { _Pragma("unroll") for (int _i = 0; _i < 2; ++_i) \
;         __builtin_amdgcn_global_load_lds((const unsigned*)((const char*)(gbase) + (voff)[_i]), (PG8_LAS unsigned*)(lds + (bufoff) + ldsw + _i * 8192), 16, 0, 0); } while (0)
; #define PG8_LDA(dst, b, h) do { _Pragma("unroll") for (int m = 0; m < 4; ++m) _Pragma("unroll") for (int k = 0; k < 2; ++k) dst[m][k] = *(const PG8_LAS bf16x8*)(lds + PG8_SA(b, h) + aoff + m * 2048 + k * 1024); } while (0)
; #define PG8_LDB(dst, b, h) do { _Pragma("unroll") for (int n = 0; n < 2; ++n) _Pragma("unroll") for (int k = 0; k < 2; ++k) dst[n][k] = *(const PG8_LAS bf16x8*)(lds + PG8_SB(b, h) + boff + n * 2048 + k * 1024); } while (0)
; #define PG8_MMA(ai, bj, At, Bt) do { __builtin_amdgcn_s_setprio(1); _Pragma("unroll") for (int m = 0; m < 4; ++m) _Pragma("unroll") for (int n = 0; n < 2; ++n) _Pragma("unroll") for (int k = 0; k < 2; ++k) \
;         acc[ai][bj][m][n] = __builtin_amdgcn_mfma_f32_16x16x32_bf16(Bt[n][k], At[m][k], acc[ai][bj][m][n], 0, 0, 0); __builtin_amdgcn_s_setprio(0); } while (0)
; #define PG8_WAIT_V(n) asm volatile("s_waitcnt vmcnt(" #n ")" ::: "memory")
; #define PG8_WAIT_L(n) asm volatile("s_waitcnt lgkmcnt(" #n ")" ::: "memory")
; #define PG8_BAR __builtin_amdgcn_s_barrier()
; #define PG8_SCHED __builtin_amdgcn_sched_barrier(0)
; template <class Epi, class Sched, bool ALIGN_EPI = false, bool SP2 = false>
; __device__ __forceinline__ void gemm_phase(PG8_LAS unsigned char* lds, const Gemm g, const Sched& S, const Epi& E) {
;     ...
;             PG8_WAIT_V(8); PG8_WAIT_L(0); PG8_BAR; PG8_MMA(1, 0, At, B0); PG8_MMA(1, 1, At, B1); PG8_BAR; PG8_SCHED;
;             PG8_LDB(B0, 1, 0); PG8_LDB(B1, 1, 1); PG8_SCHED; PG8_LDA(At, 1, 0); PG8_STAGE(PG8_SA(0, 1), a2 + hstep, voffA);
;             PG8_WAIT_V(8); PG8_WAIT_L(0); PG8_BAR; PG8_MMA(0, 0, At, B0); PG8_MMA(0, 1, At, B1); PG8_BAR; PG8_SCHED;
	v_mfma_f32_16x16x32_bf16 v[56:59], v[148:151], v[184:187], v[56:59]
	v_mfma_f32_16x16x32_bf16 v[60:63], v[156:159], v[184:187], v[60:63]
	v_mfma_f32_16x16x32_bf16 v[44:47], v[148:151], v[192:195], v[44:47]
	v_mfma_f32_16x16x32_bf16 v[40:43], v[156:159], v[192:195], v[40:43]
	v_mfma_f32_16x16x32_bf16 v[32:35], v[148:151], v[200:203], v[32:35]
	v_mfma_f32_16x16x32_bf16 v[24:27], v[156:159], v[200:203], v[24:27]
	v_mfma_f32_16x16x32_bf16 v[16:19], v[148:151], v[208:211], v[16:19]
	v_mfma_f32_16x16x32_bf16 v[8:11], v[156:159], v[208:211], v[8:11]
	v_mfma_f32_16x16x32_bf16 v[56:59], v[152:155], v[188:191], v[56:59]
	v_mfma_f32_16x16x32_bf16 v[60:63], v[160:163], v[188:191], v[60:63]
	v_mfma_f32_16x16x32_bf16 v[44:47], v[152:155], v[196:199], v[44:47]
	v_mfma_f32_16x16x32_bf16 v[40:43], v[160:163], v[196:199], v[40:43]
	v_mfma_f32_16x16x32_bf16 v[32:35], v[152:155], v[204:207], v[32:35]
	v_mfma_f32_16x16x32_bf16 v[24:27], v[160:163], v[204:207], v[24:27]
	v_mfma_f32_16x16x32_bf16 v[16:19], v[152:155], v[212:215], v[16:19]
	v_mfma_f32_16x16x32_bf16 v[8:11], v[160:163], v[212:215], v[8:11]
	v_mfma_f32_16x16x32_bf16 v[52:55], v[164:167], v[184:187], v[52:55]
	v_mfma_f32_16x16x32_bf16 v[48:51], v[172:175], v[184:187], v[48:51]
	v_mfma_f32_16x16x32_bf16 v[36:39], v[164:167], v[192:195], v[36:39]
	v_mfma_f32_16x16x32_bf16 v[28:31], v[172:175], v[192:195], v[28:31]
	v_mfma_f32_16x16x32_bf16 v[20:23], v[164:167], v[200:203], v[20:23]
	v_mfma_f32_16x16x32_bf16 v[12:15], v[172:175], v[200:203], v[12:15]
	v_mfma_f32_16x16x32_bf16 v[4:7], v[164:167], v[208:211], v[4:7]
	v_mfma_f32_16x16x32_bf16 v[0:3], v[172:175], v[208:211], v[0:3]
	v_mfma_f32_16x16x32_bf16 v[52:55], v[168:171], v[188:191], v[52:55]
	v_mfma_f32_16x16x32_bf16 v[48:51], v[176:179], v[188:191], v[48:51]
	v_mfma_f32_16x16x32_bf16 v[36:39], v[168:171], v[196:199], v[36:39]
	v_mfma_f32_16x16x32_bf16 v[28:31], v[176:179], v[196:199], v[28:31]
	v_mfma_f32_16x16x32_bf16 v[20:23], v[168:171], v[204:207], v[20:23]
	v_mfma_f32_16x16x32_bf16 v[12:15], v[176:179], v[204:207], v[12:15]
	v_mfma_f32_16x16x32_bf16 v[4:7], v[168:171], v[212:215], v[4:7]
	v_mfma_f32_16x16x32_bf16 v[0:3], v[176:179], v[212:215], v[0:3]
	s_barrier
	s_setprio 0
	s_add_i32 s46, 0, 0x18000
	v_add_u32_e32 v147, s46, v145
	s_add_i32 s47, 0, 0x1c000
	ds_read_b128 v[148:151], v147
	ds_read_b128 v[152:155], v147 offset:1024
	ds_read_b128 v[156:159], v147 offset:2048
	ds_read_b128 v[160:163], v147 offset:3072
	v_add_u32_e32 v147, s47, v145
	ds_read_b128 v[164:167], v147
	ds_read_b128 v[168:171], v147 offset:1024
	ds_read_b128 v[172:175], v147 offset:2048
	ds_read_b128 v[176:179], v147 offset:3072
	s_add_u32 s22, s22, 0x160000
	s_addc_u32 s23, s23, 0
	s_mov_b32 m0, s30
	v_lshl_add_u64 v[226:227], s[22:23], 0, v[130:131]
	ds_read_b128 v[184:187], v146 offset:32768
	ds_read_b128 v[188:191], v146 offset:33792
	ds_read_b128 v[192:195], v146 offset:34816
	ds_read_b128 v[196:199], v146 offset:35840
	ds_read_b128 v[200:203], v146 offset:36864
	ds_read_b128 v[204:207], v146 offset:37888
	ds_read_b128 v[208:211], v146 offset:38912
	ds_read_b128 v[212:215], v146 offset:39936
	global_load_lds_dwordx4 v[226:227], off
	v_lshl_add_u64 v[226:227], s[22:23], 0, v[128:129]
	s_mov_b32 m0, s31
	s_nop 0
	global_load_lds_dwordx4 v[226:227], off
	s_waitcnt vmcnt(8)
	s_waitcnt lgkmcnt(0)
	s_setprio 1
	s_barrier
	v_mfma_f32_16x16x32_bf16 v[124:127], v[148:151], v[184:187], v[124:127]
	v_mfma_f32_16x16x32_bf16 v[120:123], v[156:159], v[184:187], v[120:123]
	v_mfma_f32_16x16x32_bf16 v[108:111], v[148:151], v[192:195], v[108:111]
	v_mfma_f32_16x16x32_bf16 v[104:107], v[156:159], v[192:195], v[104:107]
	v_mfma_f32_16x16x32_bf16 v[96:99], v[148:151], v[200:203], v[96:99]
	v_mfma_f32_16x16x32_bf16 v[88:91], v[156:159], v[200:203], v[88:91]
	v_mfma_f32_16x16x32_bf16 v[80:83], v[148:151], v[208:211], v[80:83]
	v_mfma_f32_16x16x32_bf16 v[72:75], v[156:159], v[208:211], v[72:75]
	v_mfma_f32_16x16x32_bf16 v[124:127], v[152:155], v[188:191], v[124:127]
	v_mfma_f32_16x16x32_bf16 v[120:123], v[160:163], v[188:191], v[120:123]
	v_mfma_f32_16x16x32_bf16 v[108:111], v[152:155], v[196:199], v[108:111]
	v_mfma_f32_16x16x32_bf16 v[104:107], v[160:163], v[196:199], v[104:107]
	v_mfma_f32_16x16x32_bf16 v[96:99], v[152:155], v[204:207], v[96:99]
	v_mfma_f32_16x16x32_bf16 v[88:91], v[160:163], v[204:207], v[88:91]
	v_mfma_f32_16x16x32_bf16 v[80:83], v[152:155], v[212:215], v[80:83]
	v_mfma_f32_16x16x32_bf16 v[72:75], v[160:163], v[212:215], v[72:75]
	v_mfma_f32_16x16x32_bf16 v[116:119], v[164:167], v[184:187], v[116:119]
	v_mfma_f32_16x16x32_bf16 v[112:115], v[172:175], v[184:187], v[112:115]
	v_mfma_f32_16x16x32_bf16 v[100:103], v[164:167], v[192:195], v[100:103]
	v_mfma_f32_16x16x32_bf16 v[92:95], v[172:175], v[192:195], v[92:95]
	v_mfma_f32_16x16x32_bf16 v[84:87], v[164:167], v[200:203], v[84:87]
	v_mfma_f32_16x16x32_bf16 v[76:79], v[172:175], v[200:203], v[76:79]
	v_mfma_f32_16x16x32_bf16 v[68:71], v[164:167], v[208:211], v[68:71]
	v_mfma_f32_16x16x32_bf16 v[64:67], v[172:175], v[208:211], v[64:67]
	v_mfma_f32_16x16x32_bf16 v[116:119], v[168:171], v[188:191], v[116:119]
	v_mfma_f32_16x16x32_bf16 v[112:115], v[176:179], v[188:191], v[112:115]
	v_mfma_f32_16x16x32_bf16 v[100:103], v[168:171], v[196:199], v[100:103]
	v_mfma_f32_16x16x32_bf16 v[92:95], v[176:179], v[196:199], v[92:95]
	v_mfma_f32_16x16x32_bf16 v[84:87], v[168:171], v[204:207], v[84:87]
	v_mfma_f32_16x16x32_bf16 v[76:79], v[176:179], v[204:207], v[76:79]
	v_mfma_f32_16x16x32_bf16 v[68:71], v[168:171], v[212:215], v[68:71]
	v_mfma_f32_16x16x32_bf16 v[64:67], v[176:179], v[212:215], v[64:67]
	s_barrier
; #define PG8_STAGE(bufoff, gbase, voff) do { _Pragma("unroll") for (int _i = 0; _i < 2; ++_i) \
;         __builtin_amdgcn_global_load_lds((const unsigned*)((const char*)(gbase) + (voff)[_i]), (PG8_LAS unsigned*)(lds + (bufoff) + ldsw + _i * 8192), 16, 0, 0); } while (0)
; #define PG8_LDA(dst, b, h) do { _Pragma("unroll") for (int m = 0; m < 4; ++m) _Pragma("unroll") for (int k = 0; k < 2; ++k) dst[m][k] = *(const PG8_LAS bf16x8*)(lds + PG8_SA(b, h) + aoff + m * 2048 + k * 1024); } while (0)
; #define PG8_MMA(ai, bj, At, Bt) do { __builtin_amdgcn_s_setprio(1); _Pragma("unroll") for (int m = 0; m < 4; ++m) _Pragma("unroll") for (int n = 0; n < 2; ++n) _Pragma("unroll") for (int k = 0; k < 2; ++k) \
;         acc[ai][bj][m][n] = __builtin_amdgcn_mfma_f32_16x16x32_bf16(Bt[n][k], At[m][k], acc[ai][bj][m][n], 0, 0, 0); __builtin_amdgcn_s_setprio(0); } while (0)
; #define PG8_WAIT_V(n) asm volatile("s_waitcnt vmcnt(" #n ")" ::: "memory")
; #define PG8_WAIT_L(n) asm volatile("s_waitcnt lgkmcnt(" #n ")" ::: "memory")
; #define PG8_BAR __builtin_amdgcn_s_barrier()
; #define PG8_SCHED __builtin_amdgcn_sched_barrier(0)
; template <class Epi, class Sched, bool ALIGN_EPI = false, bool SP2 = false>
; __device__ __forceinline__ void gemm_phase(PG8_LAS unsigned char* lds, const Gemm g, const Sched& S, const Epi& E) {
;     ...
;             PG8_LDA(At, 1, 1); PG8_STAGE(PG8_SB(1, 0), b3, voffB); PG8_STAGE(PG8_SB(1, 1), b3 + hstep, voffB); PG8_STAGE(PG8_SA(1, 0), a3, voffA);
;             PG8_WAIT_V(8); PG8_WAIT_L(0); PG8_BAR; PG8_MMA(1, 0, At, B0); PG8_MMA(1, 1, At, B1); PG8_BAR; PG8_SCHED;
;     ...
; #pragma unroll
;         for (int a = 0; a < 2; ++a)
; #pragma unroll
;             for (int b = 0; b < 2; ++b)
; #pragma unroll
;                 for (int m = 0; m < 4; ++m)
; #pragma unroll
;                     for (int n = 0; n < 2; ++n) acc[a][b][m][n] = (f32x4){0.f, 0.f, 0.f, 0.f};
;         cur = nxt; cA = nA; cB = nB; ++ui;
	s_setprio 0
	s_add_i32 s22, s46, s27
	v_lshl_add_u64 v[180:181], v[180:181], 0, s[12:13]
	s_mov_b32 m0, s22
	ds_read_b128 v[184:187], v146 offset:49152
	ds_read_b128 v[188:191], v146 offset:50176
	ds_read_b128 v[192:195], v146 offset:51200
	ds_read_b128 v[196:199], v146 offset:52224
	ds_read_b128 v[200:203], v146 offset:53248
	ds_read_b128 v[204:207], v146 offset:54272
	ds_read_b128 v[208:211], v146 offset:55296
	ds_read_b128 v[212:215], v146 offset:56320
	global_load_lds_dwordx4 v[180:181], off
	s_add_i32 m0, s22, 0x2000
	s_add_u32 s20, s20, 0x160080
	v_lshl_add_u64 v[180:181], v[216:217], 0, s[12:13]
	s_addc_u32 s21, s21, 0
	s_add_i32 s22, s47, s27
	global_load_lds_dwordx4 v[180:181], off
	v_lshl_add_u64 v[180:181], s[20:21], 0, v[130:131]
	s_mov_b32 m0, s22
	s_nop 0
	global_load_lds_dwordx4 v[180:181], off
	v_lshl_add_u64 v[180:181], s[20:21], 0, v[128:129]
	s_add_i32 m0, s22, 0x2000
	s_nop 0
	global_load_lds_dwordx4 v[180:181], off
	v_lshl_add_u64 v[180:181], v[218:219], 0, s[12:13]
	s_mov_b32 m0, s35
	s_nop 0
	global_load_lds_dwordx4 v[180:181], off
	v_lshl_add_u64 v[180:181], v[220:221], 0, s[12:13]
	s_mov_b32 m0, s36
	s_nop 0
	global_load_lds_dwordx4 v[180:181], off
	s_waitcnt vmcnt(8)
	s_waitcnt lgkmcnt(0)
	s_setprio 1
	s_barrier
	v_mfma_f32_16x16x32_bf16 v[56:59], v[148:151], v[184:187], v[56:59]
	v_mfma_f32_16x16x32_bf16 v[60:63], v[156:159], v[184:187], v[60:63]
	v_mfma_f32_16x16x32_bf16 v[44:47], v[148:151], v[192:195], v[44:47]
	v_mfma_f32_16x16x32_bf16 v[40:43], v[156:159], v[192:195], v[40:43]
	v_mfma_f32_16x16x32_bf16 v[32:35], v[148:151], v[200:203], v[32:35]
	v_mfma_f32_16x16x32_bf16 v[24:27], v[156:159], v[200:203], v[24:27]
	v_mfma_f32_16x16x32_bf16 v[16:19], v[148:151], v[208:211], v[16:19]
	v_mfma_f32_16x16x32_bf16 v[8:11], v[156:159], v[208:211], v[8:11]
	v_mfma_f32_16x16x32_bf16 v[56:59], v[152:155], v[188:191], v[56:59]
	v_mfma_f32_16x16x32_bf16 v[60:63], v[160:163], v[188:191], v[60:63]
	v_mfma_f32_16x16x32_bf16 v[44:47], v[152:155], v[196:199], v[44:47]
	v_mfma_f32_16x16x32_bf16 v[40:43], v[160:163], v[196:199], v[40:43]
	v_mfma_f32_16x16x32_bf16 v[32:35], v[152:155], v[204:207], v[32:35]
	v_mfma_f32_16x16x32_bf16 v[24:27], v[160:163], v[204:207], v[24:27]
	v_mfma_f32_16x16x32_bf16 v[16:19], v[152:155], v[212:215], v[16:19]
	v_mfma_f32_16x16x32_bf16 v[8:11], v[160:163], v[212:215], v[8:11]
	v_mfma_f32_16x16x32_bf16 v[52:55], v[164:167], v[184:187], v[52:55]
	v_mfma_f32_16x16x32_bf16 v[48:51], v[172:175], v[184:187], v[48:51]
	v_mfma_f32_16x16x32_bf16 v[36:39], v[164:167], v[192:195], v[36:39]
	v_mfma_f32_16x16x32_bf16 v[28:31], v[172:175], v[192:195], v[28:31]
	v_mfma_f32_16x16x32_bf16 v[20:23], v[164:167], v[200:203], v[20:23]
	v_mfma_f32_16x16x32_bf16 v[12:15], v[172:175], v[200:203], v[12:15]
	v_mfma_f32_16x16x32_bf16 v[4:7], v[164:167], v[208:211], v[4:7]
	v_mfma_f32_16x16x32_bf16 v[0:3], v[172:175], v[208:211], v[0:3]
	v_mfma_f32_16x16x32_bf16 v[52:55], v[168:171], v[188:191], v[52:55]
	v_mfma_f32_16x16x32_bf16 v[48:51], v[176:179], v[188:191], v[48:51]
	v_mfma_f32_16x16x32_bf16 v[36:39], v[168:171], v[196:199], v[36:39]
	v_mfma_f32_16x16x32_bf16 v[28:31], v[176:179], v[196:199], v[28:31]
	v_mfma_f32_16x16x32_bf16 v[20:23], v[168:171], v[204:207], v[20:23]
	v_mfma_f32_16x16x32_bf16 v[12:15], v[176:179], v[204:207], v[12:15]
	v_mfma_f32_16x16x32_bf16 v[4:7], v[168:171], v[212:215], v[4:7]
	v_mfma_f32_16x16x32_bf16 v[0:3], v[176:179], v[212:215], v[0:3]
	s_barrier
	s_setprio 0
	s_add_i32 s45, s45, 2
	s_add_u32 s18, s18, 0x100
	s_addc_u32 s19, s19, 0
	s_cmpk_gt_u32 s45, 0x55
	s_cbranch_scc0 .LBB0_1205
	s_add_u32 s18, s15, 0xffffff00
	s_addc_u32 s19, s44, -1
	s_and_b64 vcc, exec, s[4:5]
	s_cbranch_vccnz .LBB0_1192
	v_mov_b64_e32 v[0:1], 0
	v_mov_b64_e32 v[2:3], 0
	v_mov_b64_e32 v[4:5], 0
	v_mov_b64_e32 v[6:7], 0
	v_mov_b64_e32 v[8:9], 0
	v_mov_b64_e32 v[10:11], 0
	v_mov_b64_e32 v[12:13], 0
	v_mov_b64_e32 v[14:15], 0
	v_mov_b64_e32 v[16:17], 0
	v_mov_b64_e32 v[18:19], 0
	v_mov_b64_e32 v[20:21], 0
	v_mov_b64_e32 v[22:23], 0
	v_mov_b64_e32 v[24:25], 0
	v_mov_b64_e32 v[26:27], 0
	v_mov_b64_e32 v[28:29], 0
	v_mov_b64_e32 v[30:31], 0
	v_mov_b64_e32 v[32:33], 0
	v_mov_b64_e32 v[34:35], 0
	v_mov_b64_e32 v[36:37], 0
	v_mov_b64_e32 v[38:39], 0
	v_mov_b64_e32 v[40:41], 0
	v_mov_b64_e32 v[42:43], 0
	v_mov_b64_e32 v[44:45], 0
	v_mov_b64_e32 v[46:47], 0
	v_mov_b64_e32 v[48:49], 0
	v_mov_b64_e32 v[50:51], 0
	v_mov_b64_e32 v[52:53], 0
	v_mov_b64_e32 v[54:55], 0
	v_mov_b64_e32 v[56:57], 0
	v_mov_b64_e32 v[58:59], 0
	v_mov_b64_e32 v[60:61], 0
	v_mov_b64_e32 v[62:63], 0
	v_mov_b64_e32 v[64:65], 0
	v_mov_b64_e32 v[66:67], 0
	v_mov_b64_e32 v[68:69], 0
	v_mov_b64_e32 v[70:71], 0
	v_mov_b64_e32 v[72:73], 0
	v_mov_b64_e32 v[74:75], 0
	v_mov_b64_e32 v[76:77], 0
	v_mov_b64_e32 v[78:79], 0
	v_mov_b64_e32 v[80:81], 0
	v_mov_b64_e32 v[82:83], 0
	v_mov_b64_e32 v[84:85], 0
	v_mov_b64_e32 v[86:87], 0
	v_mov_b64_e32 v[88:89], 0
	v_mov_b64_e32 v[90:91], 0
	v_mov_b64_e32 v[92:93], 0
	v_mov_b64_e32 v[94:95], 0
	v_mov_b64_e32 v[96:97], 0
	v_mov_b64_e32 v[98:99], 0
	v_mov_b64_e32 v[100:101], 0
	v_mov_b64_e32 v[102:103], 0
	v_mov_b64_e32 v[104:105], 0
	v_mov_b64_e32 v[106:107], 0
	v_mov_b64_e32 v[108:109], 0
	v_mov_b64_e32 v[110:111], 0
	v_mov_b64_e32 v[112:113], 0
	v_mov_b64_e32 v[114:115], 0
	v_mov_b64_e32 v[116:117], 0
	v_mov_b64_e32 v[118:119], 0
	v_mov_b64_e32 v[120:121], 0
	v_mov_b64_e32 v[122:123], 0
	v_mov_b64_e32 v[124:125], 0
	v_mov_b64_e32 v[126:127], 0
	s_mov_b32 s8, s42
	s_mov_b32 s25, s43
	s_mov_b64 s[10:11], s[16:17]
	s_mov_b32 s37, s14
	s_andn2_b64 vcc, exec, s[0:1]
	s_cbranch_vccnz .LBB0_1193
